# attention hh0: sub-tile B rescale test moved below the first 8 exps of sub-tile A to cover its exchange latency
# baseline (speedup 1.0000x reference)
; #define LAS __attribute__((address_space(3)))
; #define MFMA32(a, b, c) __builtin_amdgcn_mfma_f32_32x32x16_bf16((a), (b), (c), 0, 0, 0)
; #define AT_LMAX(P, MX) do { MX = fmaxf(fmaxf(P[0], P[1]), fmaxf(P[2], P[3])); \
;         _Pragma("unroll") for (int i_ = 4; i_ < 16; i_ += 4) MX = fmaxf(fmaxf(MX, P[i_]), fmaxf(fmaxf(P[i_ + 1], P[i_ + 2]), P[i_ + 3])); } while (0)
; __device__ __forceinline__ void attn_unit(LAS unsigned char* lds, const GAS bf16_t* __restrict__ QR, const GAS float* __restrict__ ssq, const GAS float* __restrict__ RT, const GAS bf16_t* __restrict__ K, const GAS bf16_t* __restrict__ Vt, GAS bf16_t* __restrict__ A2, int b, int h, int qb, int tid, i ...
;     ...
;             for (int d0 = 0; d0 < 6; ++d0) { const bf16x8 a0 = *(const LAS bf16x8*)(kb + d0 * 32); pA = MFMA32(a0, qa[d0], pA); pB = MFMA32(a0, qc[d0], pB); }
;             u32x4 pwA0, pwA1, pwB0, pwB1;
;             float mxA, mxB; AT_LMAX(pA, mxA); AT_LMAX(pB, mxB);
;             { const float oa = __shfl_xor(mxA, 32), ob = __shfl_xor(mxB, 32); mxA = fmaxf(mxA, oa); mxB = fmaxf(mxB, ob); }
;             AT_SOFTMAX(pA, mxA, mA, lA, oA0, oA1, pwA0, pwA1);
;             AT_SOFTMAX(pB, mxB, mB, lB, oB0, oB1, pwB0, pwB1);
.LBB0_139:
	s_mul_i32 s22, s1, 0x5800
	s_add_i32 s24, s22, 0
	v_add_u32_e32 v212, s24, v1
	ds_read_b128 v[66:69], v212
	ds_read_b128 v[214:217], v212 offset:32
	ds_read_b128 v[218:221], v212 offset:64
	ds_read_b128 v[222:225], v212 offset:96
	ds_read_b128 v[226:229], v212 offset:128
	ds_read_b128 v[230:233], v212 offset:160
	s_waitcnt lgkmcnt(5)
	v_mfma_f32_32x32x16_bf16 v[82:97], v[66:69], v[98:101], v[188:203]
	s_waitcnt lgkmcnt(4)
	v_mfma_f32_32x32x16_bf16 v[82:97], v[214:217], v[102:105], v[82:97]
	s_waitcnt lgkmcnt(3)
	v_mfma_f32_32x32x16_bf16 v[82:97], v[218:221], v[106:109], v[82:97]
	s_waitcnt lgkmcnt(2)
	v_mfma_f32_32x32x16_bf16 v[82:97], v[222:225], v[110:113], v[82:97]
	s_waitcnt lgkmcnt(1)
	v_mfma_f32_32x32x16_bf16 v[82:97], v[226:229], v[134:137], v[82:97]
	s_waitcnt lgkmcnt(0)
	v_mfma_f32_32x32x16_bf16 v[82:97], v[230:233], v[114:117], v[82:97]
	v_mfma_f32_32x32x16_bf16 v[66:81], v[66:69], v[118:121], v[234:249]
	v_mfma_f32_32x32x16_bf16 v[66:81], v[214:217], v[122:125], v[66:81]
	v_mfma_f32_32x32x16_bf16 v[66:81], v[218:221], v[126:129], v[66:81]
	v_mfma_f32_32x32x16_bf16 v[66:81], v[222:225], v[130:133], v[66:81]
	v_mfma_f32_32x32x16_bf16 v[66:81], v[226:229], v[138:141], v[66:81]
	v_mfma_f32_32x32x16_bf16 v[66:81], v[230:233], v[142:145], v[66:81]
	s_nop 5
	v_max_f32_e32 v210, v84, v85
	v_max3_f32 v210, v82, v83, v210
	v_max3_f32 v213, v87, v88, v89
	v_max3_f32 v214, v91, v92, v93
	v_max3_f32 v210, v210, v86, v213
	v_max3_f32 v215, v95, v96, v97
	v_max3_f32 v210, v210, v90, v214
	v_max3_f32 v214, v210, v94, v215
	ds_bpermute_b32 v215, v153, v214
	v_max_f32_e32 v216, v68, v69
	v_max3_f32 v216, v66, v67, v216
	v_max3_f32 v217, v71, v72, v73
	v_max3_f32 v216, v216, v70, v217
	v_max3_f32 v217, v75, v76, v77
	v_max3_f32 v210, v216, v74, v217
	v_max3_f32 v213, v79, v80, v81
	v_max3_f32 v251, v210, v78, v213
	ds_bpermute_b32 v252, v153, v251
	s_waitcnt lgkmcnt(1)
	v_max_f32_e32 v214, v214, v215
	v_cmp_lt_f32_e32 vcc, s100, v214
	s_cbranch_vccz .LBB0_141
	v_max_f32_e32 v215, s101, v214
	v_max_f32_e32 v214, 0, v215
	v_exp_f32_e64 v214, -v214
	v_sub_f32_e32 v188, v188, v215
	v_sub_f32_e32 v189, v189, v215
	v_sub_f32_e32 v190, v190, v215
	v_sub_f32_e32 v191, v191, v215
	v_sub_f32_e32 v192, v192, v215
	v_sub_f32_e32 v193, v193, v215
	v_sub_f32_e32 v194, v194, v215
	v_sub_f32_e32 v195, v195, v215
	v_sub_f32_e32 v196, v196, v215
	v_sub_f32_e32 v197, v197, v215
	v_sub_f32_e32 v198, v198, v215
	v_sub_f32_e32 v199, v199, v215
	v_sub_f32_e32 v200, v200, v215
	v_sub_f32_e32 v201, v201, v215
	v_sub_f32_e32 v202, v202, v215
	v_sub_f32_e32 v203, v203, v215
	v_sub_f32_e32 v82, v82, v215
	v_sub_f32_e32 v83, v83, v215
	v_sub_f32_e32 v84, v84, v215
	v_sub_f32_e32 v85, v85, v215
	v_sub_f32_e32 v86, v86, v215
	v_sub_f32_e32 v87, v87, v215
	v_sub_f32_e32 v88, v88, v215
	v_sub_f32_e32 v89, v89, v215
	v_sub_f32_e32 v90, v90, v215
	v_sub_f32_e32 v91, v91, v215
	v_sub_f32_e32 v92, v92, v215
	v_sub_f32_e32 v93, v93, v215
	v_sub_f32_e32 v94, v94, v215
	v_sub_f32_e32 v95, v95, v215
	v_sub_f32_e32 v96, v96, v215
	v_sub_f32_e32 v97, v97, v215
	v_pk_mul_f32 v[64:65], v[64:65], v[214:215] op_sel_hi:[1,0]
	v_pk_mul_f32 v[62:63], v[62:63], v[214:215] op_sel_hi:[1,0]
	v_pk_mul_f32 v[60:61], v[60:61], v[214:215] op_sel_hi:[1,0]
	v_pk_mul_f32 v[58:59], v[58:59], v[214:215] op_sel_hi:[1,0]
	v_pk_mul_f32 v[56:57], v[56:57], v[214:215] op_sel_hi:[1,0]
	v_pk_mul_f32 v[54:55], v[54:55], v[214:215] op_sel_hi:[1,0]
	v_pk_mul_f32 v[52:53], v[52:53], v[214:215] op_sel_hi:[1,0]
	v_pk_mul_f32 v[50:51], v[50:51], v[214:215] op_sel_hi:[1,0]
	v_pk_mul_f32 v[48:49], v[48:49], v[214:215] op_sel_hi:[1,0]
	v_pk_mul_f32 v[46:47], v[46:47], v[214:215] op_sel_hi:[1,0]
	v_pk_mul_f32 v[44:45], v[44:45], v[214:215] op_sel_hi:[1,0]
	v_pk_mul_f32 v[42:43], v[42:43], v[214:215] op_sel_hi:[1,0]
	v_pk_mul_f32 v[40:41], v[40:41], v[214:215] op_sel_hi:[1,0]
	v_pk_mul_f32 v[38:39], v[38:39], v[214:215] op_sel_hi:[1,0]
	v_pk_mul_f32 v[36:37], v[36:37], v[214:215] op_sel_hi:[1,0]
	v_pk_mul_f32 v[34:35], v[34:35], v[214:215] op_sel_hi:[1,0]
	v_mul_f32_e32 v211, v211, v214
.LBB0_141:
	v_exp_f32_e32 v210, v82
	v_exp_f32_e32 v213, v83
	v_exp_f32_e32 v214, v84
	v_exp_f32_e32 v215, v85
	v_exp_f32_e32 v216, v86
	v_exp_f32_e32 v217, v87
	v_exp_f32_e32 v218, v88
	v_exp_f32_e32 v219, v89
	v_cvt_pk_bf16_f32 v86, v210, v213
	v_exp_f32_e32 v90, v90
	v_add_f32_e32 v210, v213, v210
	v_exp_f32_e32 v91, v91
	v_add_f32_e32 v210, v214, v210
	v_exp_f32_e32 v92, v92
	v_add_f32_e32 v210, v215, v210
	v_exp_f32_e32 v93, v93
	v_add_f32_e32 v210, v216, v210
	s_waitcnt lgkmcnt(0)
	v_max_f32_e32 v251, v251, v252
	v_cmp_lt_f32_e32 vcc, s100, v251
	s_cbranch_vccz .LBB0_143
	v_max_f32_e32 v252, s101, v251
	v_max_f32_e32 v250, 0, v252
	v_exp_f32_e64 v250, -v250
	v_sub_f32_e32 v234, v234, v252
	v_sub_f32_e32 v235, v235, v252
	v_sub_f32_e32 v236, v236, v252
	v_sub_f32_e32 v237, v237, v252
	v_sub_f32_e32 v238, v238, v252
	v_sub_f32_e32 v239, v239, v252
	v_sub_f32_e32 v240, v240, v252
	v_sub_f32_e32 v241, v241, v252
	v_sub_f32_e32 v242, v242, v252
	v_sub_f32_e32 v243, v243, v252
	v_sub_f32_e32 v244, v244, v252
	v_sub_f32_e32 v245, v245, v252
	v_sub_f32_e32 v246, v246, v252
	v_sub_f32_e32 v247, v247, v252
	v_sub_f32_e32 v248, v248, v252
	v_sub_f32_e32 v249, v249, v252
	v_sub_f32_e32 v66, v66, v252
	v_sub_f32_e32 v67, v67, v252
	v_sub_f32_e32 v68, v68, v252
	v_sub_f32_e32 v69, v69, v252
	v_sub_f32_e32 v70, v70, v252
	v_sub_f32_e32 v71, v71, v252
	v_sub_f32_e32 v72, v72, v252
	v_sub_f32_e32 v73, v73, v252
	v_sub_f32_e32 v74, v74, v252
	v_sub_f32_e32 v75, v75, v252
	v_sub_f32_e32 v76, v76, v252
	v_sub_f32_e32 v77, v77, v252
	v_sub_f32_e32 v78, v78, v252
	v_sub_f32_e32 v79, v79, v252
	v_sub_f32_e32 v80, v80, v252
	v_sub_f32_e32 v81, v81, v252
	v_pk_mul_f32 v[32:33], v[32:33], v[250:251] op_sel_hi:[1,0]
	v_pk_mul_f32 v[30:31], v[30:31], v[250:251] op_sel_hi:[1,0]
	v_pk_mul_f32 v[28:29], v[28:29], v[250:251] op_sel_hi:[1,0]
	v_pk_mul_f32 v[26:27], v[26:27], v[250:251] op_sel_hi:[1,0]
	v_pk_mul_f32 v[24:25], v[24:25], v[250:251] op_sel_hi:[1,0]
	v_pk_mul_f32 v[22:23], v[22:23], v[250:251] op_sel_hi:[1,0]
	v_pk_mul_f32 v[20:21], v[20:21], v[250:251] op_sel_hi:[1,0]
	v_pk_mul_f32 v[18:19], v[18:19], v[250:251] op_sel_hi:[1,0]
	v_pk_mul_f32 v[16:17], v[16:17], v[250:251] op_sel_hi:[1,0]
	v_pk_mul_f32 v[14:15], v[14:15], v[250:251] op_sel_hi:[1,0]
	v_pk_mul_f32 v[12:13], v[12:13], v[250:251] op_sel_hi:[1,0]
	v_pk_mul_f32 v[10:11], v[10:11], v[250:251] op_sel_hi:[1,0]
	v_pk_mul_f32 v[8:9], v[8:9], v[250:251] op_sel_hi:[1,0]
	v_pk_mul_f32 v[6:7], v[6:7], v[250:251] op_sel_hi:[1,0]
	v_pk_mul_f32 v[4:5], v[4:5], v[250:251] op_sel_hi:[1,0]
	v_pk_mul_f32 v[2:3], v[2:3], v[250:251] op_sel_hi:[1,0]
	v_mul_f32_e32 v209, v209, v250
; #define LAS __attribute__((address_space(3)))
; #define MFMA32(a, b, c) __builtin_amdgcn_mfma_f32_32x32x16_bf16((a), (b), (c), 0, 0, 0)
; #define AT_LMAX(P, MX) do { MX = fmaxf(fmaxf(P[0], P[1]), fmaxf(P[2], P[3])); \
;         _Pragma("unroll") for (int i_ = 4; i_ < 16; i_ += 4) MX = fmaxf(fmaxf(MX, P[i_]), fmaxf(fmaxf(P[i_ + 1], P[i_ + 2]), P[i_ + 3])); } while (0)
; __device__ __forceinline__ void attn_unit(LAS unsigned char* lds, const GAS bf16_t* __restrict__ QR, const GAS float* __restrict__ ssq, const GAS float* __restrict__ RT, const GAS bf16_t* __restrict__ K, const GAS bf16_t* __restrict__ Vt, GAS bf16_t* __restrict__ A2, int b, int h, int qb, int tid, i ...
;     ...
;             for (int d0 = 0; d0 < 6; ++d0) { const bf16x8 a0 = *(const LAS bf16x8*)(kb + d0 * 32); pA = MFMA32(a0, qa[d0], pA); pB = MFMA32(a0, qc[d0], pB); }
;             u32x4 pwA0, pwA1, pwB0, pwB1;
;             float mxA, mxB; AT_LMAX(pA, mxA); AT_LMAX(pB, mxB);
;             { const float oa = __shfl_xor(mxA, 32), ob = __shfl_xor(mxB, 32); mxA = fmaxf(mxA, oa); mxB = fmaxf(mxB, ob); }
;             AT_SOFTMAX(pA, mxA, mA, lA, oA0, oA1, pwA0, pwA1);
;             AT_SOFTMAX(pB, mxB, mB, lB, oB0, oB1, pwB0, pwB1);
;             const LAS unsigned char* vb = sb + AT_VOFF + r32 * AT_VROW + hi * 16 + hh * 64;
; #pragma unroll
;             for (int ks = 0; ks < 2; ++ks) {
;                 const bf16x8 va0 = *(const LAS bf16x8*)(vb + ks * 32), va1 = *(const LAS bf16x8*)(vb + 32 * AT_VROW + ks * 32);
;                 const bf16x8 pa = __builtin_bit_cast(bf16x8, ks ? pwA1 : pwA0), pb = __builtin_bit_cast(bf16x8, ks ? pwB1 : pwB0);
;                 oA0 = MFMA32(va0, pa, oA0); oA1 = MFMA32(va1, pa, oA1); oB0 = MFMA32(va0, pb, oB0); oB1 = MFMA32(va1, pb, oB1);
;             }
.LBB0_143:
	s_mov_b32 s100, 0x41000000
	s_mov_b32 s101, 0
	v_exp_f32_e32 v213, v66
	v_exp_f32_e32 v94, v94
	v_cvt_pk_bf16_f32 v87, v214, v215
	v_add_f32_e32 v210, v217, v210
	v_exp_f32_e32 v214, v67
	v_exp_f32_e32 v95, v95
	v_add_f32_e32 v210, v218, v210
	v_exp_f32_e32 v215, v68
	v_exp_f32_e32 v96, v96
	v_cvt_pk_bf16_f32 v88, v216, v217
	v_add_f32_e32 v210, v219, v210
	v_exp_f32_e32 v216, v69
	v_exp_f32_e32 v97, v97
	v_cvt_pk_bf16_f32 v82, v90, v91
	v_add_f32_e32 v90, v90, v210
	v_exp_f32_e32 v217, v70
	v_cvt_pk_bf16_f32 v89, v218, v219
	v_add_f32_e32 v90, v91, v90
	v_exp_f32_e32 v218, v71
	v_add_f32_e32 v90, v92, v90
	v_exp_f32_e32 v219, v72
	v_add_f32_e32 v90, v93, v90
	v_exp_f32_e32 v220, v73
	v_add_f32_e32 v90, v94, v90
	v_exp_f32_e32 v221, v74
	v_add_f32_e32 v90, v95, v90
	v_exp_f32_e32 v222, v75
	v_add_f32_e32 v90, v96, v90
	v_exp_f32_e32 v223, v76
	v_add_f32_e32 v90, v97, v90
	v_exp_f32_e32 v224, v77
	v_add_f32_e32 v211, v211, v90
	v_exp_f32_e32 v225, v78
	v_exp_f32_e32 v226, v79
	v_add_u32_e32 v210, s24, v204
	v_cvt_pk_bf16_f32 v83, v92, v93
	v_exp_f32_e32 v227, v80
	v_exp_f32_e32 v228, v81
	ds_read_b128 v[74:77], v210 offset:17920
	ds_read_b128 v[78:81], v210 offset:13312
	ds_read_b128 v[90:93], v210 offset:13344
	v_cvt_pk_bf16_f32 v70, v213, v214
	v_cvt_pk_bf16_f32 v71, v215, v216
	v_cvt_pk_bf16_f32 v72, v217, v218
	v_cvt_pk_bf16_f32 v73, v219, v220
	s_waitcnt lgkmcnt(1)
	v_mfma_f32_32x32x16_bf16 v[50:65], v[78:81], v[86:89], v[50:65]
	v_cvt_pk_bf16_f32 v84, v94, v95
	v_cvt_pk_bf16_f32 v85, v96, v97
	v_cvt_pk_bf16_f32 v66, v221, v222
	v_cvt_pk_bf16_f32 v67, v223, v224
	v_cvt_pk_bf16_f32 v68, v225, v226
	v_cvt_pk_bf16_f32 v69, v227, v228
	v_mfma_f32_32x32x16_bf16 v[18:33], v[78:81], v[70:73], v[18:33]
	v_mfma_f32_32x32x16_bf16 v[2:17], v[74:77], v[70:73], v[2:17]
	v_add_f32_e32 v213, v214, v213
	v_add_f32_e32 v213, v215, v213
	v_add_f32_e32 v213, v216, v213
	v_add_f32_e32 v213, v217, v213
	v_add_f32_e32 v213, v218, v213
	v_add_f32_e32 v213, v219, v213
	v_add_f32_e32 v213, v220, v213
	v_add_f32_e32 v213, v221, v213
	v_add_f32_e32 v213, v222, v213
	v_add_f32_e32 v213, v223, v213
	v_add_f32_e32 v213, v224, v213
	v_add_f32_e32 v213, v225, v213
	v_add_f32_e32 v213, v226, v213
	v_add_f32_e32 v213, v227, v213
	v_add_f32_e32 v213, v228, v213
	v_add_f32_e32 v209, v209, v213
	ds_read_b128 v[70:73], v210 offset:17952
	v_mfma_f32_32x32x16_bf16 v[34:49], v[74:77], v[86:89], v[34:49]
	s_waitcnt lgkmcnt(1)
	v_mfma_f32_32x32x16_bf16 v[50:65], v[90:93], v[82:85], v[50:65]
	s_waitcnt lgkmcnt(0)
	v_mfma_f32_32x32x16_bf16 v[34:49], v[70:73], v[82:85], v[34:49]
	ds_read_b128 v[82:85], v212 offset:6656
	ds_read_b128 v[230:233], v212 offset:6688
	ds_read_b128 v[214:217], v212 offset:6720
	ds_read_b128 v[218:221], v212 offset:6752
	ds_read_b128 v[222:225], v212 offset:6784
	ds_read_b128 v[226:229], v212 offset:6816
	v_mfma_f32_32x32x16_bf16 v[18:33], v[90:93], v[66:69], v[18:33]
	v_mfma_f32_32x32x16_bf16 v[2:17], v[70:73], v[66:69], v[2:17]
	s_waitcnt lgkmcnt(5)
	v_mfma_f32_32x32x16_bf16 v[66:81], v[82:85], v[98:101], v[188:203]
	s_waitcnt lgkmcnt(4)
	v_mfma_f32_32x32x16_bf16 v[66:81], v[230:233], v[102:105], v[66:81]
	s_waitcnt lgkmcnt(3)
	v_mfma_f32_32x32x16_bf16 v[66:81], v[214:217], v[106:109], v[66:81]
	s_waitcnt lgkmcnt(2)
	v_mfma_f32_32x32x16_bf16 v[66:81], v[218:221], v[110:113], v[66:81]
	s_waitcnt lgkmcnt(1)
	v_mfma_f32_32x32x16_bf16 v[66:81], v[222:225], v[134:137], v[66:81]
	s_waitcnt lgkmcnt(0)
	v_mfma_f32_32x32x16_bf16 v[66:81], v[226:229], v[114:117], v[66:81]
	v_mfma_f32_32x32x16_bf16 v[82:97], v[82:85], v[118:121], v[234:249]
	v_mfma_f32_32x32x16_bf16 v[82:97], v[230:233], v[122:125], v[82:97]
	v_mfma_f32_32x32x16_bf16 v[82:97], v[214:217], v[126:129], v[82:97]
	v_mfma_f32_32x32x16_bf16 v[82:97], v[218:221], v[130:133], v[82:97]
	v_mfma_f32_32x32x16_bf16 v[82:97], v[222:225], v[138:141], v[82:97]
	v_mfma_f32_32x32x16_bf16 v[82:97], v[226:229], v[142:145], v[82:97]
	s_nop 5
	v_max_f32_e32 v250, v68, v69
	v_max3_f32 v179, v66, v67, v250
	v_max3_f32 v250, v71, v72, v73
	v_max3_f32 v251, v75, v76, v77
	v_max3_f32 v179, v179, v70, v250
	v_max3_f32 v252, v79, v80, v81
	v_max3_f32 v179, v179, v74, v251
	v_max3_f32 v230, v179, v78, v252
	ds_bpermute_b32 v231, v153, v230
	v_max_f32_e32 v212, v84, v85
	v_max3_f32 v212, v82, v83, v212
	v_max3_f32 v250, v87, v88, v89
	v_max3_f32 v212, v212, v86, v250
	v_max3_f32 v250, v91, v92, v93
	v_max3_f32 v212, v212, v90, v250
	v_max3_f32 v250, v95, v96, v97
	v_max3_f32 v212, v212, v94, v250
	ds_bpermute_b32 v179, v153, v212
	s_waitcnt lgkmcnt(1)
	v_max_f32_e32 v230, v230, v231
	v_cmp_lt_f32_e32 vcc, s100, v230
	s_cbranch_vccz .LBB0_145
	v_max_f32_e32 v231, s101, v230
	v_max_f32_e32 v230, 0, v231
	v_exp_f32_e64 v230, -v230
	v_sub_f32_e32 v188, v188, v231
	v_sub_f32_e32 v189, v189, v231
	v_sub_f32_e32 v190, v190, v231
	v_sub_f32_e32 v191, v191, v231
	v_sub_f32_e32 v192, v192, v231
	v_sub_f32_e32 v193, v193, v231
	v_sub_f32_e32 v194, v194, v231
	v_sub_f32_e32 v195, v195, v231
	v_sub_f32_e32 v196, v196, v231
	v_sub_f32_e32 v197, v197, v231
	v_sub_f32_e32 v198, v198, v231
	v_sub_f32_e32 v199, v199, v231
	v_sub_f32_e32 v200, v200, v231
	v_sub_f32_e32 v201, v201, v231
	v_sub_f32_e32 v202, v202, v231
	v_sub_f32_e32 v203, v203, v231
	v_sub_f32_e32 v66, v66, v231
	v_sub_f32_e32 v67, v67, v231
	v_sub_f32_e32 v68, v68, v231
	v_sub_f32_e32 v69, v69, v231
	v_sub_f32_e32 v70, v70, v231
	v_sub_f32_e32 v71, v71, v231
	v_sub_f32_e32 v72, v72, v231
	v_sub_f32_e32 v73, v73, v231
	v_sub_f32_e32 v74, v74, v231
	v_sub_f32_e32 v75, v75, v231
	v_sub_f32_e32 v76, v76, v231
	v_sub_f32_e32 v77, v77, v231
	v_sub_f32_e32 v78, v78, v231
	v_sub_f32_e32 v79, v79, v231
	v_sub_f32_e32 v80, v80, v231
	v_sub_f32_e32 v81, v81, v231
	v_pk_mul_f32 v[64:65], v[64:65], v[230:231] op_sel_hi:[1,0]
	v_pk_mul_f32 v[62:63], v[62:63], v[230:231] op_sel_hi:[1,0]
	v_pk_mul_f32 v[60:61], v[60:61], v[230:231] op_sel_hi:[1,0]
	v_pk_mul_f32 v[58:59], v[58:59], v[230:231] op_sel_hi:[1,0]
	v_pk_mul_f32 v[56:57], v[56:57], v[230:231] op_sel_hi:[1,0]
	v_pk_mul_f32 v[54:55], v[54:55], v[230:231] op_sel_hi:[1,0]
	v_pk_mul_f32 v[52:53], v[52:53], v[230:231] op_sel_hi:[1,0]
	v_pk_mul_f32 v[50:51], v[50:51], v[230:231] op_sel_hi:[1,0]
	v_pk_mul_f32 v[48:49], v[48:49], v[230:231] op_sel_hi:[1,0]
	v_pk_mul_f32 v[46:47], v[46:47], v[230:231] op_sel_hi:[1,0]
	v_pk_mul_f32 v[44:45], v[44:45], v[230:231] op_sel_hi:[1,0]
	v_pk_mul_f32 v[42:43], v[42:43], v[230:231] op_sel_hi:[1,0]
	v_pk_mul_f32 v[40:41], v[40:41], v[230:231] op_sel_hi:[1,0]
	v_pk_mul_f32 v[38:39], v[38:39], v[230:231] op_sel_hi:[1,0]
	v_pk_mul_f32 v[36:37], v[36:37], v[230:231] op_sel_hi:[1,0]
	v_pk_mul_f32 v[34:35], v[34:35], v[230:231] op_sel_hi:[1,0]
	v_mul_f32_e32 v211, v211, v230
